# v44 + exp range-clamp removal extended to prep phase silu (32 more cmp+cndmask pairs)
# speedup vs baseline: 1.0026x; 1.0001x over previous
; DEVI float bflo(unsigned w) { return __uint_as_float(w << 16); }
; DEVI float bfhi(unsigned w) { return __uint_as_float(w & 0xffff0000u); }
; DEVI float siluf(float x) { return x / (1.f + expf(-x)); }
; DEVI void phase_prep(const Params& p, int l) {
;     ...
;   for (int r = gw; r < RP; r += nw) {
;     if (l == 1 && rr_of(r) >= SEQ) continue;
;     u32x2 ga[4], gb[4], gr[4]; unsigned da[8], db[8];
; #pragma unroll
;     for (int u = 0; u < 4; ++u) {
;       const long off = (long)r * 1024 + u * 256 + lane * 4;
;       ga[u] = *(const u32x2*)(og0 + off); gb[u] = *(const u32x2*)(og1 + off);
;       gr[u] = *(const u32x2*)(feat + (long)r * NF + F_GR + u * 256 + lane * 4);
;     }
; #pragma unroll
;     for (int h = 0; h < 8; ++h) {
;       const long off = (long)r * 1024 + h * 128 + lane * 2;
;       da[h] = *(const unsigned*)(od0 + off); db[h] = *(const unsigned*)(od1 + off);
;     }
;     float o[4][4], ss[4], e0[8], e1[8], sd[8];
; #pragma unroll
;     for (int u = 0; u < 4; ++u) {
;       o[u][0] = bflo(ga[u][0]) + bflo(gb[u][0]); o[u][1] = bfhi(ga[u][0]) + bfhi(gb[u][0]);
;       o[u][2] = bflo(ga[u][1]) + bflo(gb[u][1]); o[u][3] = bfhi(ga[u][1]) + bfhi(gb[u][1]);
;       ss[u] = o[u][0] * o[u][0] + o[u][1] * o[u][1] + o[u][2] * o[u][2] + o[u][3] * o[u][3];
;     }
; #pragma unroll
;     for (int h = 0; h < 8; ++h) {
;       e0[h] = bflo(da[h]) - lam * bflo(db[h]); e1[h] = bfhi(da[h]) - lam * bfhi(db[h]);
;       sd[h] = e0[h] * e0[h] + e1[h] * e1[h];
;     }
; #pragma unroll
;     for (int m = 32; m >= 1; m >>= 1) {
; #pragma unroll
;       for (int u = 0; u < 4; ++u) ss[u] += __shfl_xor(ss[u], m);
; #pragma unroll
;       for (int h = 0; h < 8; ++h) sd[h] += __shfl_xor(sd[h], m);
;     }
; #pragma unroll
;     for (int u = 0; u < 4; ++u) {
;       const float rsd = rsqrtf(ss[u] * (1.f / 256.f) + EPS);
;       const float rv[4] = {bflo(gr[u][0]), bfhi(gr[u][0]), bflo(gr[u][1]), bfhi(gr[u][1])};
;       float y[4];
; #pragma unroll
;       for (int j = 0; j < 4; ++j) y[j] = o[u][j] * rsd * gg[j] * siluf(rv[j]);
.LBB0_497:
	s_and_saveexec_b64 s[10:11], s[2:3]
	s_cbranch_execz .LBB0_494
	v_lshl_add_u64 v[18:19], s[90:91], 0, v[10:11]
	v_add_co_u32_e32 v42, vcc, 0x22bec000, v18
	v_lshl_add_u64 v[16:17], s[90:91], 0, v[6:7]
	s_nop 0
	v_addc_co_u32_e32 v43, vcc, 0, v19, vcc
	v_add_co_u32_e32 v18, vcc, 0x24cec000, v18
	global_load_dwordx2 v[72:73], v[42:43], off offset:2048
	s_nop 0
	v_addc_co_u32_e32 v19, vcc, 0, v19, vcc
	v_add_co_u32_e32 v16, vcc, 0x7eed000, v16
	global_load_dwordx2 v[78:79], v[18:19], off offset:2048
	s_nop 0
	v_addc_co_u32_e32 v17, vcc, 0, v17, vcc
	global_load_dwordx2 v[74:75], v[16:17], off offset:2048
	global_load_dwordx2 v[68:69], v[42:43], off offset:2560
	global_load_dwordx2 v[66:67], v[18:19], off offset:2560
	global_load_dwordx2 v[52:53], v[16:17], off offset:2560
	global_load_dwordx2 v[64:65], v[42:43], off offset:3072
	global_load_dwordx2 v[62:63], v[18:19], off offset:3072
	global_load_dwordx2 v[60:61], v[16:17], off offset:3072
	global_load_dwordx2 v[58:59], v[42:43], off offset:3584
	global_load_dwordx2 v[56:57], v[18:19], off offset:3584
	global_load_dwordx2 v[54:55], v[16:17], off offset:3584
	v_lshl_add_u64 v[18:19], s[90:91], 0, v[8:9]
	s_mov_b32 s2, 0x26dec000
	v_add_co_u32_e32 v16, vcc, s2, v18
	s_mov_b32 s2, 0x28eec000
	s_nop 0
	v_addc_co_u32_e32 v17, vcc, 0, v19, vcc
	v_add_co_u32_e32 v18, vcc, s2, v18
	global_load_dword v5, v[16:17], off offset:2048
	s_nop 0
	v_addc_co_u32_e32 v19, vcc, 0, v19, vcc
	global_load_dword v20, v[18:19], off offset:2048
	global_load_dword v21, v[16:17], off offset:2304
	global_load_dword v22, v[18:19], off offset:2304
	global_load_dword v23, v[16:17], off offset:2560
	global_load_dword v24, v[18:19], off offset:2560
	global_load_dword v25, v[16:17], off offset:2816
	global_load_dword v26, v[18:19], off offset:2816
	global_load_dword v27, v[16:17], off offset:3072
	global_load_dword v29, v[18:19], off offset:3072
	global_load_dword v31, v[16:17], off offset:3328
	global_load_dword v33, v[18:19], off offset:3328
	global_load_dword v70, v[16:17], off offset:3584
	global_load_dword v71, v[18:19], off offset:3584
	global_load_dword v76, v[16:17], off offset:3840
	global_load_dword v77, v[18:19], off offset:3840
	s_waitcnt vmcnt(25)
	v_and_b32_e32 v82, 0xffff0000, v75
	v_lshlrev_b32_e32 v80, 16, v72
	v_and_b32_e32 v81, 0xffff0000, v72
	s_waitcnt vmcnt(24)
	v_lshlrev_b32_e32 v88, 16, v68
	v_and_b32_e32 v89, 0xffff0000, v68
	s_waitcnt vmcnt(23)
	v_lshlrev_b32_e32 v68, 16, v66
	v_lshlrev_b32_e32 v72, 16, v78
	s_waitcnt vmcnt(14)
	v_lshlrev_b32_e32 v46, 16, v20
	v_and_b32_e32 v47, 0xffff0000, v20
	s_waitcnt vmcnt(13)
	v_lshlrev_b32_e32 v48, 16, v21
	v_and_b32_e32 v49, 0xffff0000, v21
	s_waitcnt vmcnt(12)
	v_lshlrev_b32_e32 v50, 16, v22
	v_and_b32_e32 v51, 0xffff0000, v22
	s_waitcnt vmcnt(11)
	v_lshlrev_b32_e32 v34, 16, v23
	s_waitcnt vmcnt(10)
	v_lshlrev_b32_e32 v36, 16, v24
	v_and_b32_e32 v35, 0xffff0000, v23
	v_and_b32_e32 v37, 0xffff0000, v24
	s_waitcnt vmcnt(9)
	v_lshlrev_b32_e32 v38, 16, v25
	s_waitcnt vmcnt(3)
	v_lshlrev_b32_e32 v18, 16, v70
	s_waitcnt vmcnt(2)
	v_lshlrev_b32_e32 v20, 16, v71
	v_and_b32_e32 v19, 0xffff0000, v70
	v_and_b32_e32 v21, 0xffff0000, v71
	v_lshlrev_b32_e32 v70, 16, v73
	v_and_b32_e32 v71, 0xffff0000, v73
	v_and_b32_e32 v73, 0xffff0000, v78
	v_pk_add_f32 v[72:73], v[80:81], v[72:73]
	v_lshlrev_b32_e32 v80, 16, v74
	v_and_b32_e32 v81, 0xffff0000, v74
	v_mul_f32_e32 v74, 0xbfb8aa3b, v80
	v_lshlrev_b32_e32 v44, 16, v5
	v_and_b32_e32 v45, 0xffff0000, v5
	v_lshlrev_b32_e32 v5, 16, v75
	v_fma_f32 v75, v80, s54, -v74
	v_rndne_f32_e32 v83, v74
	v_fmac_f32_e32 v75, 0xb2a5705f, v80
	v_sub_f32_e32 v74, v74, v83
	v_add_f32_e32 v74, v74, v75
	v_exp_f32_e32 v74, v74
	v_cvt_i32_f32_e32 v75, v83
	v_and_b32_e32 v39, 0xffff0000, v25
	s_waitcnt vmcnt(1)
	v_lshlrev_b32_e32 v22, 16, v76
	v_ldexp_f32 v74, v74, v75
	v_mul_f32_e32 v75, 0xbfb8aa3b, v81
	v_fma_f32 v83, v81, s54, -v75
	v_rndne_f32_e32 v84, v75
	v_fmac_f32_e32 v83, 0xb2a5705f, v81
	v_sub_f32_e32 v75, v75, v84
	v_add_f32_e32 v75, v75, v83
	v_exp_f32_e32 v75, v75
	v_cvt_i32_f32_e32 v83, v84
	s_waitcnt vmcnt(0)
	v_lshlrev_b32_e32 v24, 16, v77
	v_ldexp_f32 v75, v75, v83
	v_and_b32_e32 v23, 0xffff0000, v76
	v_and_b32_e32 v25, 0xffff0000, v77
	v_lshlrev_b32_e32 v76, 16, v79
	v_and_b32_e32 v77, 0xffff0000, v79
	v_pk_add_f32 v[74:75], v[74:75], 1.0 op_sel_hi:[1,0]
	v_pk_add_f32 v[70:71], v[70:71], v[76:77]
	v_div_scale_f32 v83, s[2:3], v75, v75, v81
	v_rcp_f32_e32 v84, v83
	v_pk_mul_f32 v[78:79], v[72:73], v[72:73]
	v_pk_mul_f32 v[76:77], v[70:71], v[70:71]
	v_lshlrev_b32_e32 v40, 16, v26
	v_fma_f32 v85, -v83, v84, 1.0
	v_fmac_f32_e32 v84, v85, v84
	v_div_scale_f32 v85, vcc, v81, v75, v81
	v_mul_f32_e32 v86, v85, v84
	v_fma_f32 v87, -v83, v86, v85
	v_fmac_f32_e32 v86, v87, v84
	v_fma_f32 v83, -v83, v86, v85
	v_div_fmas_f32 v83, v83, v84, v86
	v_div_fixup_f32 v75, v83, v75, v81
	v_div_scale_f32 v81, s[2:3], v74, v74, v80
	v_rcp_f32_e32 v83, v81
	v_and_b32_e32 v41, 0xffff0000, v26
	v_pk_fma_f32 v[34:35], v[12:13], v[36:37], v[34:35] neg_lo:[1,0,0] neg_hi:[1,0,0]
	v_pk_fma_f32 v[38:39], v[12:13], v[40:41], v[38:39] neg_lo:[1,0,0] neg_hi:[1,0,0]
	v_fma_f32 v84, -v81, v83, 1.0
	v_fmac_f32_e32 v83, v84, v83
	v_div_scale_f32 v84, vcc, v80, v74, v80
	v_mul_f32_e32 v85, v84, v83
	v_fma_f32 v86, -v81, v85, v84
	v_fmac_f32_e32 v85, v86, v83
	v_fma_f32 v81, -v81, v85, v84
	v_div_fmas_f32 v81, v81, v83, v85
	v_div_fixup_f32 v74, v81, v74, v80
	v_mul_f32_e32 v80, 0xbfb8aa3b, v5
	v_fma_f32 v81, v5, s54, -v80
	v_rndne_f32_e32 v83, v80
	v_fmac_f32_e32 v81, 0xb2a5705f, v5
	v_sub_f32_e32 v80, v80, v83
	v_add_f32_e32 v80, v80, v81
	v_exp_f32_e32 v80, v80
; DEVI float bflo(unsigned w) { return __uint_as_float(w << 16); }
; DEVI float bfhi(unsigned w) { return __uint_as_float(w & 0xffff0000u); }
; DEVI float siluf(float x) { return x / (1.f + expf(-x)); }
; DEVI void phase_prep(const Params& p, int l) {
;     ...
;     for (int u = 0; u < 4; ++u) {
;       o[u][0] = bflo(ga[u][0]) + bflo(gb[u][0]); o[u][1] = bfhi(ga[u][0]) + bfhi(gb[u][0]);
;       o[u][2] = bflo(ga[u][1]) + bflo(gb[u][1]); o[u][3] = bfhi(ga[u][1]) + bfhi(gb[u][1]);
;       ss[u] = o[u][0] * o[u][0] + o[u][1] * o[u][1] + o[u][2] * o[u][2] + o[u][3] * o[u][3];
;     }
; #pragma unroll
;     for (int h = 0; h < 8; ++h) {
;       e0[h] = bflo(da[h]) - lam * bflo(db[h]); e1[h] = bfhi(da[h]) - lam * bfhi(db[h]);
;       sd[h] = e0[h] * e0[h] + e1[h] * e1[h];
;     }
; #pragma unroll
;     for (int m = 32; m >= 1; m >>= 1) {
; #pragma unroll
;       for (int u = 0; u < 4; ++u) ss[u] += __shfl_xor(ss[u], m);
; #pragma unroll
;       for (int h = 0; h < 8; ++h) sd[h] += __shfl_xor(sd[h], m);
;     }
;     ...
;       for (int j = 0; j < 4; ++j) y[j] = o[u][j] * rsd * gg[j] * siluf(rv[j]);
	v_cvt_i32_f32_e32 v81, v83
	v_pk_mul_f32 v[36:37], v[34:35], v[34:35]
	v_pk_mul_f32 v[40:41], v[38:39], v[38:39]
	v_ldexp_f32 v80, v80, v81
	v_mul_f32_e32 v81, 0xbfb8aa3b, v82
	v_fma_f32 v83, v82, s54, -v81
	v_rndne_f32_e32 v84, v81
	v_fmac_f32_e32 v83, 0xb2a5705f, v82
	v_sub_f32_e32 v81, v81, v84
	v_add_f32_e32 v81, v81, v83
	v_exp_f32_e32 v81, v81
	v_cvt_i32_f32_e32 v83, v84
	v_lshlrev_b32_e32 v26, 16, v27
	v_ldexp_f32 v81, v81, v83
	v_lshlrev_b32_e32 v28, 16, v29
	v_and_b32_e32 v27, 0xffff0000, v27
	v_and_b32_e32 v29, 0xffff0000, v29
	v_lshlrev_b32_e32 v30, 16, v31
	v_pk_add_f32 v[80:81], v[80:81], 1.0 op_sel_hi:[1,0]
	v_lshlrev_b32_e32 v32, 16, v33
	v_div_scale_f32 v83, s[2:3], v81, v81, v82
	v_rcp_f32_e32 v84, v83
	v_and_b32_e32 v31, 0xffff0000, v31
	v_and_b32_e32 v33, 0xffff0000, v33
	v_pk_fma_f32 v[26:27], v[12:13], v[28:29], v[26:27] neg_lo:[1,0,0] neg_hi:[1,0,0]
	v_fma_f32 v85, -v83, v84, 1.0
	v_fmac_f32_e32 v84, v85, v84
	v_div_scale_f32 v85, vcc, v82, v81, v82
	v_mul_f32_e32 v86, v85, v84
	v_fma_f32 v87, -v83, v86, v85
	v_fmac_f32_e32 v86, v87, v84
	v_fma_f32 v83, -v83, v86, v85
	v_div_fmas_f32 v83, v83, v84, v86
	v_div_fixup_f32 v83, v83, v81, v82
	v_div_scale_f32 v81, s[2:3], v80, v80, v5
	v_rcp_f32_e32 v82, v81
	v_pk_fma_f32 v[30:31], v[12:13], v[32:33], v[30:31] neg_lo:[1,0,0] neg_hi:[1,0,0]
	v_pk_mul_f32 v[28:29], v[26:27], v[26:27]
	v_pk_mul_f32 v[32:33], v[30:31], v[30:31]
	v_fma_f32 v84, -v81, v82, 1.0
	v_fmac_f32_e32 v82, v84, v82
	v_div_scale_f32 v84, vcc, v5, v80, v5
	v_mul_f32_e32 v85, v84, v82
	v_fma_f32 v86, -v81, v85, v84
	v_fmac_f32_e32 v85, v86, v82
	v_fma_f32 v81, -v81, v85, v84
	v_div_fmas_f32 v81, v81, v82, v85
	v_div_fixup_f32 v82, v81, v80, v5
	v_lshlrev_b32_e32 v80, 16, v69
	v_and_b32_e32 v81, 0xffff0000, v69
	v_and_b32_e32 v69, 0xffff0000, v66
	v_lshlrev_b32_e32 v84, 16, v67
	v_and_b32_e32 v85, 0xffff0000, v67
	v_pk_add_f32 v[66:67], v[88:89], v[68:69]
	v_lshlrev_b32_e32 v68, 16, v52
	v_and_b32_e32 v69, 0xffff0000, v52
	v_mul_f32_e32 v52, 0xbfb8aa3b, v68
	v_pk_add_f32 v[80:81], v[80:81], v[84:85]
	v_lshlrev_b32_e32 v5, 16, v53
	v_and_b32_e32 v84, 0xffff0000, v53
	v_fma_f32 v53, v68, s54, -v52
	v_rndne_f32_e32 v85, v52
	v_fmac_f32_e32 v53, 0xb2a5705f, v68
	v_sub_f32_e32 v52, v52, v85
	v_add_f32_e32 v52, v52, v53
	v_exp_f32_e32 v52, v52
	v_cvt_i32_f32_e32 v53, v85
	v_pk_mul_f32 v[88:89], v[66:67], v[66:67]
	v_pk_mul_f32 v[86:87], v[80:81], v[80:81]
	v_ldexp_f32 v52, v52, v53
	v_mul_f32_e32 v53, 0xbfb8aa3b, v69
	v_fma_f32 v85, v69, s54, -v53
	v_rndne_f32_e32 v90, v53
	v_fmac_f32_e32 v85, 0xb2a5705f, v69
	v_sub_f32_e32 v53, v53, v90
	v_add_f32_e32 v53, v53, v85
	v_exp_f32_e32 v53, v53
	v_cvt_i32_f32_e32 v85, v90
	v_pk_fma_f32 v[18:19], v[12:13], v[20:21], v[18:19] neg_lo:[1,0,0] neg_hi:[1,0,0]
	v_ldexp_f32 v53, v53, v85
	v_pk_fma_f32 v[22:23], v[12:13], v[24:25], v[22:23] neg_lo:[1,0,0] neg_hi:[1,0,0]
	v_pk_mul_f32 v[20:21], v[18:19], v[18:19]
	v_pk_mul_f32 v[24:25], v[22:23], v[22:23]
	s_nop 0
	v_pk_add_f32 v[52:53], v[52:53], 1.0 op_sel_hi:[1,0]
	s_nop 0
	v_div_scale_f32 v85, s[2:3], v53, v53, v69
	v_rcp_f32_e32 v90, v85
	s_nop 0
	v_fma_f32 v91, -v85, v90, 1.0
	v_fmac_f32_e32 v90, v91, v90
	v_div_scale_f32 v91, vcc, v69, v53, v69
	v_mul_f32_e32 v92, v91, v90
	v_fma_f32 v93, -v85, v92, v91
	v_fmac_f32_e32 v92, v93, v90
	v_fma_f32 v85, -v85, v92, v91
	v_div_fmas_f32 v85, v85, v90, v92
	v_div_fixup_f32 v69, v85, v53, v69
	v_div_scale_f32 v53, s[2:3], v52, v52, v68
	v_rcp_f32_e32 v85, v53
	s_mov_b32 s2, 0x358637bd
	v_fma_f32 v90, -v53, v85, 1.0
	v_fmac_f32_e32 v85, v90, v85
	v_div_scale_f32 v90, vcc, v68, v52, v68
	v_mul_f32_e32 v91, v90, v85
	v_fma_f32 v92, -v53, v91, v90
	v_fmac_f32_e32 v91, v92, v85
	v_fma_f32 v53, -v53, v91, v90
	v_div_fmas_f32 v53, v53, v85, v91
	v_div_fixup_f32 v68, v53, v52, v68
	v_mov_b32_e32 v52, v88
	v_mov_b32_e32 v53, v78
	v_mov_b32_e32 v78, v89
	v_pk_add_f32 v[52:53], v[52:53], v[78:79]
	v_mov_b32_e32 v78, v86
	v_mov_b32_e32 v79, v76
	v_pk_add_f32 v[52:53], v[78:79], v[52:53]
	v_mov_b32_e32 v76, v87
	v_pk_add_f32 v[52:53], v[76:77], v[52:53]
	v_mov_b32_e32 v77, v53
	v_mov_b32_e32 v76, v52
	s_waitcnt lgkmcnt(0)
	s_nop 1
	v_permlane32_swap_b32_e32 v52, v76
	v_permlane32_swap_b32_e32 v53, v77
	v_pk_add_f32 v[52:53], v[52:53], v[76:77]
	v_mov_b32_e32 v77, v53
	v_mov_b32_e32 v76, v52
	s_waitcnt lgkmcnt(0)
	s_nop 1
	v_permlane16_swap_b32_e32 v52, v76
	v_permlane16_swap_b32_e32 v53, v77
	v_pk_add_f32 v[52:53], v[52:53], v[76:77]
	s_waitcnt lgkmcnt(0)
	s_nop 1
	v_add_f32_dpp v52, v52, v52 row_ror:8 row_mask:0xf bank_mask:0xf
	v_add_f32_dpp v53, v53, v53 row_ror:8 row_mask:0xf bank_mask:0xf
	s_waitcnt lgkmcnt(0)
	s_nop 1
	v_add_f32_dpp v52, v52, v52 row_ror:4 row_mask:0xf bank_mask:0xf
	v_add_f32_dpp v53, v53, v53 row_ror:4 row_mask:0xf bank_mask:0xf
	s_waitcnt lgkmcnt(0)
	s_nop 1
	v_add_f32_dpp v52, v52, v52 quad_perm:[2,3,0,1] row_mask:0xf bank_mask:0xf
	v_add_f32_dpp v53, v53, v53 quad_perm:[2,3,0,1] row_mask:0xf bank_mask:0xf
	s_waitcnt lgkmcnt(0)
; DEVI float bflo(unsigned w) { return __uint_as_float(w << 16); }
; DEVI float bfhi(unsigned w) { return __uint_as_float(w & 0xffff0000u); }
; DEVI void st4bf(u16* p, float a, float b, float c, float d) { u32x2 w = {cvtpk(a, b), cvtpk(c, d)}; *(u32x2*)p = w; }
; DEVI float siluf(float x) { return x / (1.f + expf(-x)); }
; DEVI void phase_prep(const Params& p, int l) {
;     ...
;     for (int u = 0; u < 4; ++u) {
;       o[u][0] = bflo(ga[u][0]) + bflo(gb[u][0]); o[u][1] = bfhi(ga[u][0]) + bfhi(gb[u][0]);
;       o[u][2] = bflo(ga[u][1]) + bflo(gb[u][1]); o[u][3] = bfhi(ga[u][1]) + bfhi(gb[u][1]);
;       ss[u] = o[u][0] * o[u][0] + o[u][1] * o[u][1] + o[u][2] * o[u][2] + o[u][3] * o[u][3];
;     }
; #pragma unroll
;     for (int h = 0; h < 8; ++h) {
;       e0[h] = bflo(da[h]) - lam * bflo(db[h]); e1[h] = bfhi(da[h]) - lam * bfhi(db[h]);
;       sd[h] = e0[h] * e0[h] + e1[h] * e1[h];
;     }
; #pragma unroll
;     for (int m = 32; m >= 1; m >>= 1) {
; #pragma unroll
;       for (int u = 0; u < 4; ++u) ss[u] += __shfl_xor(ss[u], m);
; #pragma unroll
;       for (int h = 0; h < 8; ++h) sd[h] += __shfl_xor(sd[h], m);
;     }
; #pragma unroll
;     for (int u = 0; u < 4; ++u) {
;       const float rsd = rsqrtf(ss[u] * (1.f / 256.f) + EPS);
;       const float rv[4] = {bflo(gr[u][0]), bfhi(gr[u][0]), bflo(gr[u][1]), bfhi(gr[u][1])};
;       float y[4];
; #pragma unroll
;       for (int j = 0; j < 4; ++j) y[j] = o[u][j] * rsd * gg[j] * siluf(rv[j]);
;       st4bf(ya + (long)r * 1024 + u * 256 + lane * 4, y[0], y[1], y[2], y[3]);
	s_nop 1
	v_add_f32_dpp v76, v52, v52 quad_perm:[1,0,3,2] row_mask:0xf bank_mask:0xf
	v_add_f32_dpp v77, v53, v53 quad_perm:[1,0,3,2] row_mask:0xf bank_mask:0xf
	v_mov_b64_e32 v[52:53], s[2:3]
	v_pk_fma_f32 v[76:77], v[76:77], s[26:27], v[52:53] op_sel_hi:[1,0,0]
	s_nop 0
	v_mul_f32_e32 v78, 0x4b800000, v77
	v_cmp_gt_f32_e64 s[2:3], s59, v77
	v_cmp_gt_f32_e32 vcc, s59, v76
	s_nop 0
	v_cndmask_b32_e64 v77, v77, v78, s[2:3]
	v_rsq_f32_e32 v77, v77
	s_nop 0
	v_mul_f32_e32 v78, 0x45800000, v77
	v_cndmask_b32_e64 v78, v77, v78, s[2:3]
	v_pk_mul_f32 v[72:73], v[72:73], v[78:79] op_sel_hi:[1,0]
	v_pk_mul_f32 v[70:71], v[70:71], v[78:79] op_sel_hi:[1,0]
	v_pk_mul_f32 v[72:73], v[0:1], v[72:73]
	v_pk_mul_f32 v[70:71], v[2:3], v[70:71]
	v_pk_mul_f32 v[72:73], v[74:75], v[72:73]
	v_pk_mul_f32 v[70:71], v[82:83], v[70:71]
	v_cvt_pk_bf16_f32 v72, v72, v73
	v_cvt_pk_bf16_f32 v73, v70, v71
	v_mul_f32_e32 v70, 0x4b800000, v76
	v_cndmask_b32_e32 v70, v76, v70, vcc
	v_rsq_f32_e32 v70, v70
	global_store_dwordx2 v[42:43], v[72:73], off offset:2048
	v_lshlrev_b32_e32 v78, 16, v56
	v_and_b32_e32 v79, 0xffff0000, v56
	v_mul_f32_e32 v71, 0x45800000, v70
	v_cndmask_b32_e32 v70, v70, v71, vcc
	v_pk_mul_f32 v[66:67], v[66:67], v[70:71] op_sel_hi:[1,0]
	v_pk_mul_f32 v[66:67], v[0:1], v[66:67]
	s_nop 0
	v_pk_mul_f32 v[66:67], v[68:69], v[66:67]
	v_mul_f32_e32 v68, 0xbfb8aa3b, v5
	v_fma_f32 v69, v5, s54, -v68
	v_rndne_f32_e32 v71, v68
	v_fmac_f32_e32 v69, 0xb2a5705f, v5
	v_sub_f32_e32 v68, v68, v71
	v_add_f32_e32 v68, v68, v69
	v_exp_f32_e32 v68, v68
	v_cvt_i32_f32_e32 v69, v71
	v_pk_mul_f32 v[70:71], v[80:81], v[70:71] op_sel_hi:[1,0]
	v_cvt_pk_bf16_f32 v66, v66, v67
	v_pk_mul_f32 v[70:71], v[2:3], v[70:71]
	v_ldexp_f32 v68, v68, v69
	v_mul_f32_e32 v69, 0xbfb8aa3b, v84
	v_fma_f32 v72, v84, s54, -v69
	v_rndne_f32_e32 v73, v69
	v_fmac_f32_e32 v72, 0xb2a5705f, v84
	v_sub_f32_e32 v69, v69, v73
	v_add_f32_e32 v69, v69, v72
	v_exp_f32_e32 v69, v69
	v_cvt_i32_f32_e32 v72, v73
	v_ldexp_f32 v69, v69, v72
	s_nop 0
	s_nop 1
	s_nop 1
	v_pk_add_f32 v[68:69], v[68:69], 1.0 op_sel_hi:[1,0]
	s_nop 0
	v_div_scale_f32 v72, s[2:3], v69, v69, v84
	v_rcp_f32_e32 v73, v72
	s_nop 0
	v_fma_f32 v74, -v72, v73, 1.0
	v_fmac_f32_e32 v73, v74, v73
	v_div_scale_f32 v74, vcc, v84, v69, v84
	v_mul_f32_e32 v75, v74, v73
	v_fma_f32 v76, -v72, v75, v74
	v_fmac_f32_e32 v75, v76, v73
	v_fma_f32 v72, -v72, v75, v74
	v_div_fmas_f32 v72, v72, v73, v75
	v_div_fixup_f32 v69, v72, v69, v84
	v_div_scale_f32 v72, s[2:3], v68, v68, v5
	v_rcp_f32_e32 v73, v72
	s_nop 0
	v_fma_f32 v74, -v72, v73, 1.0
	v_fmac_f32_e32 v73, v74, v73
	v_div_scale_f32 v74, vcc, v5, v68, v5
	v_mul_f32_e32 v75, v74, v73
	v_fma_f32 v76, -v72, v75, v74
	v_fmac_f32_e32 v75, v76, v73
	v_fma_f32 v72, -v72, v75, v74
	v_div_fmas_f32 v72, v72, v73, v75
	v_div_fixup_f32 v68, v72, v68, v5
	v_pk_mul_f32 v[68:69], v[68:69], v[70:71]
	v_lshlrev_b32_e32 v70, 16, v64
	v_cvt_pk_bf16_f32 v67, v68, v69
	global_store_dwordx2 v[42:43], v[66:67], off offset:2560
	v_lshlrev_b32_e32 v66, 16, v65
	v_and_b32_e32 v67, 0xffff0000, v65
	v_and_b32_e32 v71, 0xffff0000, v64
	v_lshlrev_b32_e32 v64, 16, v62
	v_and_b32_e32 v65, 0xffff0000, v62
	v_lshlrev_b32_e32 v68, 16, v63
	v_and_b32_e32 v69, 0xffff0000, v63
	v_pk_add_f32 v[62:63], v[70:71], v[64:65]
	v_lshlrev_b32_e32 v70, 16, v60
	v_and_b32_e32 v71, 0xffff0000, v60
	v_mul_f32_e32 v60, 0xbfb8aa3b, v70
	v_lshlrev_b32_e32 v5, 16, v61
	v_and_b32_e32 v72, 0xffff0000, v61
	v_fma_f32 v61, v70, s54, -v60
	v_rndne_f32_e32 v73, v60
	v_fmac_f32_e32 v61, 0xb2a5705f, v70
	v_sub_f32_e32 v60, v60, v73
	v_add_f32_e32 v60, v60, v61
	v_exp_f32_e32 v60, v60
	v_cvt_i32_f32_e32 v61, v73
	v_pk_add_f32 v[66:67], v[66:67], v[68:69]
	v_pk_mul_f32 v[64:65], v[62:63], v[62:63]
	v_ldexp_f32 v60, v60, v61
	v_mul_f32_e32 v61, 0xbfb8aa3b, v71
	v_fma_f32 v73, v71, s54, -v61
	v_rndne_f32_e32 v74, v61
	v_fmac_f32_e32 v73, 0xb2a5705f, v71
	v_sub_f32_e32 v61, v61, v74
	v_add_f32_e32 v61, v61, v73
	v_exp_f32_e32 v61, v61
	v_cvt_i32_f32_e32 v73, v74
	v_pk_mul_f32 v[68:69], v[66:67], v[66:67]
	v_ldexp_f32 v61, v61, v73
	s_nop 1
	s_nop 1
	v_pk_add_f32 v[60:61], v[60:61], 1.0 op_sel_hi:[1,0]
	s_nop 0
	v_div_scale_f32 v73, s[2:3], v61, v61, v71
	v_rcp_f32_e32 v74, v73
	s_nop 0
	v_fma_f32 v75, -v73, v74, 1.0
	v_fmac_f32_e32 v74, v75, v74
	v_div_scale_f32 v75, vcc, v71, v61, v71
	v_mul_f32_e32 v76, v75, v74
	v_fma_f32 v77, -v73, v76, v75
	v_fmac_f32_e32 v76, v77, v74
	v_fma_f32 v73, -v73, v76, v75
	v_div_fmas_f32 v73, v73, v74, v76
	v_div_fixup_f32 v61, v73, v61, v71
	v_div_scale_f32 v71, s[2:3], v60, v60, v70
	v_rcp_f32_e32 v73, v71
	s_nop 0
	v_fma_f32 v74, -v71, v73, 1.0
	v_fmac_f32_e32 v73, v74, v73
	v_div_scale_f32 v74, vcc, v70, v60, v70
	v_mul_f32_e32 v75, v74, v73
	v_fma_f32 v76, -v71, v75, v74
	v_fmac_f32_e32 v75, v76, v73
	v_fma_f32 v71, -v71, v75, v74
	v_div_fmas_f32 v71, v71, v73, v75
	v_div_fixup_f32 v60, v71, v60, v70
	v_mul_f32_e32 v70, 0xbfb8aa3b, v5
	v_fma_f32 v71, v5, s54, -v70
	v_rndne_f32_e32 v73, v70
	v_fmac_f32_e32 v71, 0xb2a5705f, v5
	v_sub_f32_e32 v70, v70, v73
	v_add_f32_e32 v70, v70, v71
	v_exp_f32_e32 v70, v70
	v_cvt_i32_f32_e32 v71, v73
	v_ldexp_f32 v70, v70, v71
	v_mul_f32_e32 v71, 0xbfb8aa3b, v72
	v_fma_f32 v73, v72, s54, -v71
	v_rndne_f32_e32 v74, v71
	v_fmac_f32_e32 v73, 0xb2a5705f, v72
	v_sub_f32_e32 v71, v71, v74
	v_add_f32_e32 v71, v71, v73
	v_exp_f32_e32 v71, v71
	v_cvt_i32_f32_e32 v73, v74
	v_ldexp_f32 v71, v71, v73
	s_nop 0
	s_nop 1
	s_nop 1
	v_pk_add_f32 v[70:71], v[70:71], 1.0 op_sel_hi:[1,0]
	s_nop 0
	v_div_scale_f32 v73, s[2:3], v71, v71, v72
	v_rcp_f32_e32 v74, v73
	s_nop 0
	v_fma_f32 v75, -v73, v74, 1.0
; DEVI float bflo(unsigned w) { return __uint_as_float(w << 16); }
; DEVI float bfhi(unsigned w) { return __uint_as_float(w & 0xffff0000u); }
; DEVI void st4bf(u16* p, float a, float b, float c, float d) { u32x2 w = {cvtpk(a, b), cvtpk(c, d)}; *(u32x2*)p = w; }
; DEVI float siluf(float x) { return x / (1.f + expf(-x)); }
; DEVI void phase_prep(const Params& p, int l) {
;     ...
;     for (int u = 0; u < 4; ++u) {
;       o[u][0] = bflo(ga[u][0]) + bflo(gb[u][0]); o[u][1] = bfhi(ga[u][0]) + bfhi(gb[u][0]);
;       o[u][2] = bflo(ga[u][1]) + bflo(gb[u][1]); o[u][3] = bfhi(ga[u][1]) + bfhi(gb[u][1]);
;       ss[u] = o[u][0] * o[u][0] + o[u][1] * o[u][1] + o[u][2] * o[u][2] + o[u][3] * o[u][3];
;     }
; #pragma unroll
;     for (int h = 0; h < 8; ++h) {
;       e0[h] = bflo(da[h]) - lam * bflo(db[h]); e1[h] = bfhi(da[h]) - lam * bfhi(db[h]);
;       sd[h] = e0[h] * e0[h] + e1[h] * e1[h];
;     }
; #pragma unroll
;     for (int m = 32; m >= 1; m >>= 1) {
; #pragma unroll
;       for (int u = 0; u < 4; ++u) ss[u] += __shfl_xor(ss[u], m);
; #pragma unroll
;       for (int h = 0; h < 8; ++h) sd[h] += __shfl_xor(sd[h], m);
;     }
; #pragma unroll
;     for (int u = 0; u < 4; ++u) {
;       const float rsd = rsqrtf(ss[u] * (1.f / 256.f) + EPS);
;       const float rv[4] = {bflo(gr[u][0]), bfhi(gr[u][0]), bflo(gr[u][1]), bfhi(gr[u][1])};
;       float y[4];
; #pragma unroll
;       for (int j = 0; j < 4; ++j) y[j] = o[u][j] * rsd * gg[j] * siluf(rv[j]);
;       st4bf(ya + (long)r * 1024 + u * 256 + lane * 4, y[0], y[1], y[2], y[3]);
	v_fmac_f32_e32 v74, v75, v74
	v_div_scale_f32 v75, vcc, v72, v71, v72
	v_mul_f32_e32 v76, v75, v74
	v_fma_f32 v77, -v73, v76, v75
	v_fmac_f32_e32 v76, v77, v74
	v_fma_f32 v73, -v73, v76, v75
	v_div_fmas_f32 v73, v73, v74, v76
	v_div_fixup_f32 v73, v73, v71, v72
	v_div_scale_f32 v71, s[2:3], v70, v70, v5
	v_rcp_f32_e32 v72, v71
	v_and_b32_e32 v77, 0xffff0000, v58
	v_fma_f32 v74, -v71, v72, 1.0
	v_fmac_f32_e32 v72, v74, v72
	v_div_scale_f32 v74, vcc, v5, v70, v5
	v_mul_f32_e32 v75, v74, v72
	v_fma_f32 v76, -v71, v75, v74
	v_fmac_f32_e32 v75, v76, v72
	v_fma_f32 v71, -v71, v75, v74
	v_lshlrev_b32_e32 v76, 16, v58
	v_lshlrev_b32_e32 v58, 16, v54
	v_div_fmas_f32 v71, v71, v72, v75
	v_lshlrev_b32_e32 v74, 16, v57
	v_and_b32_e32 v75, 0xffff0000, v57
	v_pk_add_f32 v[56:57], v[76:77], v[78:79]
	v_and_b32_e32 v78, 0xffff0000, v54
	v_mul_f32_e32 v54, 0xbfb8aa3b, v58
	v_div_fixup_f32 v72, v71, v70, v5
	v_lshlrev_b32_e32 v70, 16, v59
	v_and_b32_e32 v71, 0xffff0000, v59
	v_lshlrev_b32_e32 v5, 16, v55
	v_and_b32_e32 v59, 0xffff0000, v55
	v_fma_f32 v55, v58, s54, -v54
	v_rndne_f32_e32 v79, v54
	v_fmac_f32_e32 v55, 0xb2a5705f, v58
	v_sub_f32_e32 v54, v54, v79
	v_add_f32_e32 v54, v54, v55
	v_exp_f32_e32 v54, v54
	v_cvt_i32_f32_e32 v55, v79
	v_pk_add_f32 v[70:71], v[70:71], v[74:75]
	v_pk_mul_f32 v[76:77], v[56:57], v[56:57]
	v_ldexp_f32 v54, v54, v55
	v_mul_f32_e32 v55, 0xbfb8aa3b, v78
	v_fma_f32 v79, v78, s54, -v55
	v_rndne_f32_e32 v80, v55
	v_fmac_f32_e32 v79, 0xb2a5705f, v78
	v_sub_f32_e32 v55, v55, v80
	v_add_f32_e32 v55, v55, v79
	v_exp_f32_e32 v55, v55
	v_cvt_i32_f32_e32 v79, v80
	v_pk_mul_f32 v[74:75], v[70:71], v[70:71]
	v_ldexp_f32 v55, v55, v79
	s_nop 1
	s_nop 1
	v_pk_add_f32 v[54:55], v[54:55], 1.0 op_sel_hi:[1,0]
	s_nop 0
	v_div_scale_f32 v79, s[2:3], v55, v55, v78
	v_rcp_f32_e32 v80, v79
	s_nop 0
	v_fma_f32 v81, -v79, v80, 1.0
	v_fmac_f32_e32 v80, v81, v80
	v_div_scale_f32 v81, vcc, v78, v55, v78
	v_mul_f32_e32 v82, v81, v80
	v_fma_f32 v83, -v79, v82, v81
	v_fmac_f32_e32 v82, v83, v80
	v_fma_f32 v79, -v79, v82, v81
	v_div_fmas_f32 v79, v79, v80, v82
	v_div_fixup_f32 v55, v79, v55, v78
	v_div_scale_f32 v78, s[2:3], v54, v54, v58
	v_rcp_f32_e32 v79, v78
	s_nop 0
	v_fma_f32 v80, -v78, v79, 1.0
	v_fmac_f32_e32 v79, v80, v79
	v_div_scale_f32 v80, vcc, v58, v54, v58
	v_mul_f32_e32 v81, v80, v79
	v_fma_f32 v82, -v78, v81, v80
	v_fmac_f32_e32 v81, v82, v79
	v_fma_f32 v78, -v78, v81, v80
	v_div_fmas_f32 v78, v78, v79, v81
	v_div_fixup_f32 v54, v78, v54, v58
	v_mov_b32_e32 v78, v76
	v_mov_b32_e32 v79, v64
	v_mov_b32_e32 v64, v77
	v_pk_add_f32 v[64:65], v[78:79], v[64:65]
	v_mov_b32_e32 v76, v74
	v_mov_b32_e32 v77, v68
	v_pk_add_f32 v[64:65], v[76:77], v[64:65]
	v_mov_b32_e32 v68, v75
	v_pk_add_f32 v[64:65], v[68:69], v[64:65]
	v_mov_b32_e32 v69, v65
	v_mov_b32_e32 v68, v64
	s_waitcnt lgkmcnt(0)
	s_nop 1
	v_permlane32_swap_b32_e32 v64, v68
	v_permlane32_swap_b32_e32 v65, v69
	v_pk_add_f32 v[64:65], v[64:65], v[68:69]
	v_mov_b32_e32 v69, v65
	v_mov_b32_e32 v68, v64
	s_waitcnt lgkmcnt(0)
	s_nop 1
	v_permlane16_swap_b32_e32 v64, v68
	v_permlane16_swap_b32_e32 v65, v69
	v_pk_add_f32 v[64:65], v[64:65], v[68:69]
	s_waitcnt lgkmcnt(0)
	s_nop 1
	v_add_f32_dpp v64, v64, v64 row_ror:8 row_mask:0xf bank_mask:0xf
	v_add_f32_dpp v65, v65, v65 row_ror:8 row_mask:0xf bank_mask:0xf
	s_waitcnt lgkmcnt(0)
	s_nop 1
	v_add_f32_dpp v64, v64, v64 row_ror:4 row_mask:0xf bank_mask:0xf
	v_add_f32_dpp v65, v65, v65 row_ror:4 row_mask:0xf bank_mask:0xf
	s_waitcnt lgkmcnt(0)
	s_nop 1
	v_add_f32_dpp v64, v64, v64 quad_perm:[2,3,0,1] row_mask:0xf bank_mask:0xf
	v_add_f32_dpp v65, v65, v65 quad_perm:[2,3,0,1] row_mask:0xf bank_mask:0xf
	s_waitcnt lgkmcnt(0)
	s_nop 1
	v_add_f32_dpp v64, v64, v64 quad_perm:[1,0,3,2] row_mask:0xf bank_mask:0xf
	v_add_f32_dpp v65, v65, v65 quad_perm:[1,0,3,2] row_mask:0xf bank_mask:0xf
	s_nop 0
	v_pk_fma_f32 v[64:65], v[64:65], s[26:27], v[52:53] op_sel_hi:[1,0,0]
	s_nop 0
	v_mul_f32_e32 v58, 0x4b800000, v65
	v_cmp_gt_f32_e64 s[2:3], s59, v65
	v_cmp_gt_f32_e32 vcc, s59, v64
	s_nop 0
	v_cndmask_b32_e64 v58, v65, v58, s[2:3]
	v_rsq_f32_e32 v58, v58
	s_nop 0
	v_mul_f32_e32 v65, 0x45800000, v58
	v_cndmask_b32_e64 v58, v58, v65, s[2:3]
	v_pk_mul_f32 v[62:63], v[62:63], v[58:59] op_sel_hi:[1,0]
	s_nop 0
	v_pk_mul_f32 v[62:63], v[0:1], v[62:63]
	s_nop 0
	v_pk_mul_f32 v[60:61], v[60:61], v[62:63]
	v_pk_mul_f32 v[62:63], v[66:67], v[58:59] op_sel_hi:[1,0]
	v_mul_f32_e32 v58, 0x4b800000, v64
	v_cndmask_b32_e32 v58, v64, v58, vcc
	v_rsq_f32_e32 v58, v58
	v_pk_mul_f32 v[62:63], v[2:3], v[62:63]
	v_cvt_pk_bf16_f32 v60, v60, v61
	v_pk_mul_f32 v[62:63], v[72:73], v[62:63]
	s_nop 0
	v_cvt_pk_bf16_f32 v61, v62, v63
	global_store_dwordx2 v[42:43], v[60:61], off offset:3072
	v_mul_f32_e32 v60, 0x45800000, v58
	v_cndmask_b32_e32 v58, v58, v60, vcc
	v_pk_mul_f32 v[56:57], v[56:57], v[58:59] op_sel_hi:[1,0]
	v_pk_mul_f32 v[56:57], v[0:1], v[56:57]
	s_nop 0
	v_pk_mul_f32 v[54:55], v[54:55], v[56:57]
	v_mul_f32_e32 v56, 0xbfb8aa3b, v5
	v_fma_f32 v57, v5, s54, -v56
	v_rndne_f32_e32 v60, v56
	v_fmac_f32_e32 v57, 0xb2a5705f, v5
	v_sub_f32_e32 v56, v56, v60
	v_add_f32_e32 v56, v56, v57
	v_exp_f32_e32 v56, v56
	v_cvt_i32_f32_e32 v57, v60
	v_pk_mul_f32 v[60:61], v[70:71], v[58:59] op_sel_hi:[1,0]
	v_cvt_pk_bf16_f32 v54, v54, v55
	v_pk_mul_f32 v[60:61], v[2:3], v[60:61]
	v_ldexp_f32 v56, v56, v57
	v_mul_f32_e32 v57, 0xbfb8aa3b, v59
	v_fma_f32 v58, v59, s54, -v57
	v_rndne_f32_e32 v62, v57
	v_fmac_f32_e32 v58, 0xb2a5705f, v59
	v_sub_f32_e32 v57, v57, v62
	v_add_f32_e32 v57, v57, v58
	v_exp_f32_e32 v57, v57
	v_cvt_i32_f32_e32 v58, v62
	v_ldexp_f32 v57, v57, v58
	s_nop 0
	s_nop 1
	s_nop 1
	v_pk_add_f32 v[56:57], v[56:57], 1.0 op_sel_hi:[1,0]
	s_nop 0
	v_div_scale_f32 v58, s[2:3], v57, v57, v59
	v_rcp_f32_e32 v62, v58
	s_nop 0
	v_fma_f32 v63, -v58, v62, 1.0
	v_fmac_f32_e32 v62, v63, v62
	v_div_scale_f32 v63, vcc, v59, v57, v59
	v_mul_f32_e32 v64, v63, v62
	v_fma_f32 v65, -v58, v64, v63
	v_fmac_f32_e32 v64, v65, v62
	v_fma_f32 v58, -v58, v64, v63
	v_div_fmas_f32 v58, v58, v62, v64
	v_div_fixup_f32 v57, v58, v57, v59
	v_div_scale_f32 v58, s[2:3], v56, v56, v5
	v_rcp_f32_e32 v59, v58
	s_nop 0
	v_fma_f32 v62, -v58, v59, 1.0
	v_fmac_f32_e32 v59, v62, v59
	v_div_scale_f32 v62, vcc, v5, v56, v5
	v_mul_f32_e32 v63, v62, v59
	v_fma_f32 v64, -v58, v63, v62
	v_fmac_f32_e32 v63, v64, v59
	v_fma_f32 v58, -v58, v63, v62
	v_div_fmas_f32 v58, v58, v59, v63
	v_div_fixup_f32 v56, v58, v56, v5
	v_pk_mul_f32 v[56:57], v[56:57], v[60:61]
	s_nop 0
	v_cvt_pk_bf16_f32 v55, v56, v57
	global_store_dwordx2 v[42:43], v[54:55], off offset:3584
	v_pk_fma_f32 v[42:43], v[12:13], v[46:47], v[44:45] neg_lo:[1,0,0] neg_hi:[1,0,0]
	v_pk_fma_f32 v[46:47], v[12:13], v[50:51], v[48:49] neg_lo:[1,0,0] neg_hi:[1,0,0]
	v_pk_mul_f32 v[44:45], v[42:43], v[42:43]
	v_pk_mul_f32 v[48:49], v[46:47], v[46:47]
	v_mov_b32_e32 v51, v44
	v_mov_b32_e32 v50, v48
	v_mov_b32_e32 v44, v49
	v_pk_add_f32 v[44:45], v[50:51], v[44:45]
	v_mov_b32_e32 v49, v45
	v_mov_b32_e32 v48, v44
	s_waitcnt lgkmcnt(0)
; DEVI unsigned cvtpk(float lo, float hi) { f32x2_t v = {lo, hi}; bf16x2_t b = __builtin_convertvector(v, bf16x2_t); return __builtin_bit_cast(unsigned, b); }
; DEVI float bflo(unsigned w) { return __uint_as_float(w << 16); }
; DEVI float bfhi(unsigned w) { return __uint_as_float(w & 0xffff0000u); }
; DEVI void st4bf(u16* p, float a, float b, float c, float d) { u32x2 w = {cvtpk(a, b), cvtpk(c, d)}; *(u32x2*)p = w; }
; DEVI float siluf(float x) { return x / (1.f + expf(-x)); }
; DEVI void phase_prep(const Params& p, int l) {
;     ...
;       for (int h = 0; h < 8; ++h) sd[h] += __shfl_xor(sd[h], m);
;     }
; #pragma unroll
;     for (int u = 0; u < 4; ++u) {
;       const float rsd = rsqrtf(ss[u] * (1.f / 256.f) + EPS);
;       const float rv[4] = {bflo(gr[u][0]), bfhi(gr[u][0]), bflo(gr[u][1]), bfhi(gr[u][1])};
;       float y[4];
; #pragma unroll
;       for (int j = 0; j < 4; ++j) y[j] = o[u][j] * rsd * gg[j] * siluf(rv[j]);
;       st4bf(ya + (long)r * 1024 + u * 256 + lane * 4, y[0], y[1], y[2], y[3]);
;     }
; #pragma unroll
;     for (int h = 0; h < 8; ++h) {
;       const float rsd = rsqrtf(sd[h] * (1.f / 128.f) + EPS);
;       *(unsigned*)(yb + (long)r * 1024 + h * 128 + lane * 2) = cvtpk(e0[h] * rsd * dg0, e1[h] * rsd * dg1);
;     }
	s_nop 1
	v_permlane32_swap_b32_e32 v44, v48
	v_permlane32_swap_b32_e32 v45, v49
	v_pk_add_f32 v[44:45], v[44:45], v[48:49]
	v_mov_b32_e32 v49, v45
	v_mov_b32_e32 v48, v44
	s_waitcnt lgkmcnt(0)
	s_nop 1
	v_permlane16_swap_b32_e32 v44, v48
	v_permlane16_swap_b32_e32 v45, v49
	v_pk_add_f32 v[44:45], v[44:45], v[48:49]
	s_waitcnt lgkmcnt(0)
	s_nop 1
	v_add_f32_dpp v44, v44, v44 row_ror:8 row_mask:0xf bank_mask:0xf
	v_add_f32_dpp v45, v45, v45 row_ror:8 row_mask:0xf bank_mask:0xf
	s_waitcnt lgkmcnt(0)
	s_nop 1
	v_add_f32_dpp v44, v44, v44 row_ror:4 row_mask:0xf bank_mask:0xf
	v_add_f32_dpp v45, v45, v45 row_ror:4 row_mask:0xf bank_mask:0xf
	s_waitcnt lgkmcnt(0)
	s_nop 1
	v_add_f32_dpp v44, v44, v44 quad_perm:[2,3,0,1] row_mask:0xf bank_mask:0xf
	v_add_f32_dpp v45, v45, v45 quad_perm:[2,3,0,1] row_mask:0xf bank_mask:0xf
	s_waitcnt lgkmcnt(0)
	s_nop 1
	v_add_f32_dpp v44, v44, v44 quad_perm:[1,0,3,2] row_mask:0xf bank_mask:0xf
	v_add_f32_dpp v45, v45, v45 quad_perm:[1,0,3,2] row_mask:0xf bank_mask:0xf
	s_nop 0
	v_pk_fma_f32 v[44:45], v[44:45], s[28:29], v[52:53] op_sel_hi:[1,0,0]
	s_nop 0
	v_mul_f32_e32 v5, 0x4b800000, v45
	v_cmp_gt_f32_e64 s[2:3], s59, v45
	v_cmp_gt_f32_e32 vcc, s59, v44
	s_nop 0
	v_cndmask_b32_e64 v5, v45, v5, s[2:3]
	v_rsq_f32_e32 v5, v5
	s_nop 0
	v_mul_f32_e32 v45, 0x45800000, v5
	v_cndmask_b32_e64 v48, v5, v45, s[2:3]
	v_pk_mul_f32 v[42:43], v[42:43], v[48:49] op_sel_hi:[1,0]
	s_nop 0
	v_pk_mul_f32 v[42:43], v[14:15], v[42:43]
	s_nop 0
	v_cvt_pk_bf16_f32 v5, v42, v43
	global_store_dword v[16:17], v5, off offset:2048
	v_mul_f32_e32 v5, 0x4b800000, v44
	v_cndmask_b32_e32 v5, v44, v5, vcc
	v_rsq_f32_e32 v5, v5
	s_nop 0
	v_mul_f32_e32 v42, 0x45800000, v5
	v_cndmask_b32_e32 v42, v5, v42, vcc
	v_pk_mul_f32 v[42:43], v[46:47], v[42:43] op_sel_hi:[1,0]
	s_nop 0
	v_pk_mul_f32 v[42:43], v[14:15], v[42:43]
	s_nop 0
	v_cvt_pk_bf16_f32 v5, v42, v43
	v_mov_b32_e32 v42, v40
	v_mov_b32_e32 v43, v36
	v_mov_b32_e32 v36, v41
	v_pk_add_f32 v[36:37], v[42:43], v[36:37]
	v_mov_b32_e32 v41, v37
	v_mov_b32_e32 v40, v36
	global_store_dword v[16:17], v5, off offset:2304
	s_waitcnt lgkmcnt(0)
	s_nop 1
	v_permlane32_swap_b32_e32 v36, v40
	v_permlane32_swap_b32_e32 v37, v41
	v_pk_add_f32 v[36:37], v[36:37], v[40:41]
	v_mov_b32_e32 v41, v37
	v_mov_b32_e32 v40, v36
	s_waitcnt lgkmcnt(0)
	s_nop 1
	v_permlane16_swap_b32_e32 v36, v40
	v_permlane16_swap_b32_e32 v37, v41
	v_pk_add_f32 v[36:37], v[36:37], v[40:41]
	s_waitcnt lgkmcnt(0)
	s_nop 1
	v_add_f32_dpp v36, v36, v36 row_ror:8 row_mask:0xf bank_mask:0xf
	v_add_f32_dpp v37, v37, v37 row_ror:8 row_mask:0xf bank_mask:0xf
	s_waitcnt lgkmcnt(0)
	s_nop 1
	v_add_f32_dpp v36, v36, v36 row_ror:4 row_mask:0xf bank_mask:0xf
	v_add_f32_dpp v37, v37, v37 row_ror:4 row_mask:0xf bank_mask:0xf
	s_waitcnt lgkmcnt(0)
	s_nop 1
	v_add_f32_dpp v36, v36, v36 quad_perm:[2,3,0,1] row_mask:0xf bank_mask:0xf
	v_add_f32_dpp v37, v37, v37 quad_perm:[2,3,0,1] row_mask:0xf bank_mask:0xf
	s_waitcnt lgkmcnt(0)
	s_nop 1
	v_add_f32_dpp v36, v36, v36 quad_perm:[1,0,3,2] row_mask:0xf bank_mask:0xf
	v_add_f32_dpp v37, v37, v37 quad_perm:[1,0,3,2] row_mask:0xf bank_mask:0xf
	s_nop 0
	v_pk_fma_f32 v[36:37], v[36:37], s[28:29], v[52:53] op_sel_hi:[1,0,0]
	s_nop 0
	v_mul_f32_e32 v5, 0x4b800000, v37
	v_cmp_gt_f32_e64 s[2:3], s59, v37
	v_cmp_gt_f32_e32 vcc, s59, v36
	s_nop 0
	v_cndmask_b32_e64 v5, v37, v5, s[2:3]
	v_rsq_f32_e32 v5, v5
	s_nop 0
	v_mul_f32_e32 v37, 0x45800000, v5
	v_cndmask_b32_e64 v40, v5, v37, s[2:3]
	v_pk_mul_f32 v[34:35], v[34:35], v[40:41] op_sel_hi:[1,0]
	s_nop 0
	v_pk_mul_f32 v[34:35], v[14:15], v[34:35]
	s_nop 0
	v_cvt_pk_bf16_f32 v5, v34, v35
	global_store_dword v[16:17], v5, off offset:2560
	v_mul_f32_e32 v5, 0x4b800000, v36
	v_cndmask_b32_e32 v5, v36, v5, vcc
	v_rsq_f32_e32 v5, v5
	s_nop 0
	v_mul_f32_e32 v34, 0x45800000, v5
	v_cndmask_b32_e32 v34, v5, v34, vcc
	v_pk_mul_f32 v[34:35], v[38:39], v[34:35] op_sel_hi:[1,0]
	s_nop 0
	v_pk_mul_f32 v[34:35], v[14:15], v[34:35]
	s_nop 0
	v_cvt_pk_bf16_f32 v5, v34, v35
	v_mov_b32_e32 v34, v32
	v_mov_b32_e32 v35, v28
	v_mov_b32_e32 v28, v33
	v_pk_add_f32 v[28:29], v[34:35], v[28:29]
	v_mov_b32_e32 v33, v29
	v_mov_b32_e32 v32, v28
	global_store_dword v[16:17], v5, off offset:2816
	s_waitcnt lgkmcnt(0)
; DEVI unsigned cvtpk(float lo, float hi) { f32x2_t v = {lo, hi}; bf16x2_t b = __builtin_convertvector(v, bf16x2_t); return __builtin_bit_cast(unsigned, b); }
; DEVI float bflo(unsigned w) { return __uint_as_float(w << 16); }
; DEVI float bfhi(unsigned w) { return __uint_as_float(w & 0xffff0000u); }
; DEVI void st4bf(u16* p, float a, float b, float c, float d) { u32x2 w = {cvtpk(a, b), cvtpk(c, d)}; *(u32x2*)p = w; }
; DEVI float siluf(float x) { return x / (1.f + expf(-x)); }
; DEVI void phase_prep(const Params& p, int l) {
;     ...
;       for (int h = 0; h < 8; ++h) sd[h] += __shfl_xor(sd[h], m);
;     }
; #pragma unroll
;     for (int u = 0; u < 4; ++u) {
;       const float rsd = rsqrtf(ss[u] * (1.f / 256.f) + EPS);
;       const float rv[4] = {bflo(gr[u][0]), bfhi(gr[u][0]), bflo(gr[u][1]), bfhi(gr[u][1])};
;       float y[4];
; #pragma unroll
;       for (int j = 0; j < 4; ++j) y[j] = o[u][j] * rsd * gg[j] * siluf(rv[j]);
;       st4bf(ya + (long)r * 1024 + u * 256 + lane * 4, y[0], y[1], y[2], y[3]);
;     }
; #pragma unroll
;     for (int h = 0; h < 8; ++h) {
;       const float rsd = rsqrtf(sd[h] * (1.f / 128.f) + EPS);
;       *(unsigned*)(yb + (long)r * 1024 + h * 128 + lane * 2) = cvtpk(e0[h] * rsd * dg0, e1[h] * rsd * dg1);
;     }
	s_nop 1
	v_permlane32_swap_b32_e32 v28, v32
	v_permlane32_swap_b32_e32 v29, v33
	v_pk_add_f32 v[28:29], v[28:29], v[32:33]
	v_mov_b32_e32 v33, v29
	v_mov_b32_e32 v32, v28
	s_waitcnt lgkmcnt(0)
	s_nop 1
	v_permlane16_swap_b32_e32 v28, v32
	v_permlane16_swap_b32_e32 v29, v33
	v_pk_add_f32 v[28:29], v[28:29], v[32:33]
	s_waitcnt lgkmcnt(0)
	s_nop 1
	v_add_f32_dpp v28, v28, v28 row_ror:8 row_mask:0xf bank_mask:0xf
	v_add_f32_dpp v29, v29, v29 row_ror:8 row_mask:0xf bank_mask:0xf
	s_waitcnt lgkmcnt(0)
	s_nop 1
	v_add_f32_dpp v28, v28, v28 row_ror:4 row_mask:0xf bank_mask:0xf
	v_add_f32_dpp v29, v29, v29 row_ror:4 row_mask:0xf bank_mask:0xf
	s_waitcnt lgkmcnt(0)
	s_nop 1
	v_add_f32_dpp v28, v28, v28 quad_perm:[2,3,0,1] row_mask:0xf bank_mask:0xf
	v_add_f32_dpp v29, v29, v29 quad_perm:[2,3,0,1] row_mask:0xf bank_mask:0xf
	s_waitcnt lgkmcnt(0)
	s_nop 1
	v_add_f32_dpp v28, v28, v28 quad_perm:[1,0,3,2] row_mask:0xf bank_mask:0xf
	v_add_f32_dpp v29, v29, v29 quad_perm:[1,0,3,2] row_mask:0xf bank_mask:0xf
	s_nop 0
	v_pk_fma_f32 v[28:29], v[28:29], s[28:29], v[52:53] op_sel_hi:[1,0,0]
	s_nop 0
	v_mul_f32_e32 v5, 0x4b800000, v29
	v_cmp_gt_f32_e64 s[2:3], s59, v29
	v_cmp_gt_f32_e32 vcc, s59, v28
	s_nop 0
	v_cndmask_b32_e64 v5, v29, v5, s[2:3]
	v_rsq_f32_e32 v5, v5
	s_nop 0
	v_mul_f32_e32 v29, 0x45800000, v5
	v_cndmask_b32_e64 v32, v5, v29, s[2:3]
	v_pk_mul_f32 v[26:27], v[26:27], v[32:33] op_sel_hi:[1,0]
	s_nop 0
	v_pk_mul_f32 v[26:27], v[14:15], v[26:27]
	s_nop 0
	v_cvt_pk_bf16_f32 v5, v26, v27
	global_store_dword v[16:17], v5, off offset:3072
	v_mul_f32_e32 v5, 0x4b800000, v28
	v_cndmask_b32_e32 v5, v28, v5, vcc
	v_rsq_f32_e32 v5, v5
	s_nop 0
	v_mul_f32_e32 v26, 0x45800000, v5
	v_cndmask_b32_e32 v26, v5, v26, vcc
	v_pk_mul_f32 v[26:27], v[30:31], v[26:27] op_sel_hi:[1,0]
	s_nop 0
	v_pk_mul_f32 v[26:27], v[14:15], v[26:27]
	s_nop 0
	v_cvt_pk_bf16_f32 v5, v26, v27
	v_mov_b32_e32 v26, v24
	v_mov_b32_e32 v27, v20
	v_mov_b32_e32 v20, v25
	v_pk_add_f32 v[20:21], v[26:27], v[20:21]
	v_mov_b32_e32 v25, v21
	v_mov_b32_e32 v24, v20
	global_store_dword v[16:17], v5, off offset:3328
	s_waitcnt lgkmcnt(0)
	s_nop 1
	v_permlane32_swap_b32_e32 v20, v24
	v_permlane32_swap_b32_e32 v21, v25
	v_pk_add_f32 v[20:21], v[20:21], v[24:25]
	v_mov_b32_e32 v25, v21
	v_mov_b32_e32 v24, v20
	s_waitcnt lgkmcnt(0)
	s_nop 1
	v_permlane16_swap_b32_e32 v20, v24
	v_permlane16_swap_b32_e32 v21, v25
	v_pk_add_f32 v[20:21], v[20:21], v[24:25]
	s_waitcnt lgkmcnt(0)
	s_nop 1
	v_add_f32_dpp v20, v20, v20 row_ror:8 row_mask:0xf bank_mask:0xf
	v_add_f32_dpp v21, v21, v21 row_ror:8 row_mask:0xf bank_mask:0xf
	s_waitcnt lgkmcnt(0)
	s_nop 1
	v_add_f32_dpp v20, v20, v20 row_ror:4 row_mask:0xf bank_mask:0xf
	v_add_f32_dpp v21, v21, v21 row_ror:4 row_mask:0xf bank_mask:0xf
	s_waitcnt lgkmcnt(0)
	s_nop 1
	v_add_f32_dpp v20, v20, v20 quad_perm:[2,3,0,1] row_mask:0xf bank_mask:0xf
	v_add_f32_dpp v21, v21, v21 quad_perm:[2,3,0,1] row_mask:0xf bank_mask:0xf
	s_waitcnt lgkmcnt(0)
	s_nop 1
	v_add_f32_dpp v20, v20, v20 quad_perm:[1,0,3,2] row_mask:0xf bank_mask:0xf
	v_add_f32_dpp v21, v21, v21 quad_perm:[1,0,3,2] row_mask:0xf bank_mask:0xf
	s_nop 0
	v_pk_fma_f32 v[20:21], v[20:21], s[28:29], v[52:53] op_sel_hi:[1,0,0]
	s_nop 0
	v_mul_f32_e32 v5, 0x4b800000, v21
	v_cmp_gt_f32_e64 s[2:3], s59, v21
	v_cmp_gt_f32_e32 vcc, s59, v20
	s_nop 0
	v_cndmask_b32_e64 v5, v21, v5, s[2:3]
	v_rsq_f32_e32 v5, v5
	s_nop 0
	v_mul_f32_e32 v21, 0x45800000, v5
	v_cndmask_b32_e64 v24, v5, v21, s[2:3]
	v_pk_mul_f32 v[18:19], v[18:19], v[24:25] op_sel_hi:[1,0]
	s_nop 0
	v_pk_mul_f32 v[18:19], v[14:15], v[18:19]
	s_nop 0
	v_cvt_pk_bf16_f32 v5, v18, v19
	global_store_dword v[16:17], v5, off offset:3584
	v_mul_f32_e32 v5, 0x4b800000, v20
	v_cndmask_b32_e32 v5, v20, v5, vcc
	v_rsq_f32_e32 v5, v5
	s_nop 0
	v_mul_f32_e32 v18, 0x45800000, v5
	v_cndmask_b32_e32 v18, v5, v18, vcc
	v_pk_mul_f32 v[18:19], v[22:23], v[18:19] op_sel_hi:[1,0]
	s_nop 0
	v_pk_mul_f32 v[18:19], v[14:15], v[18:19]
	s_nop 0
	v_cvt_pk_bf16_f32 v5, v18, v19
	global_store_dword v[16:17], v5, off offset:3840
	s_branch .LBB0_494
